# combo15 + S5 final scan: one v_cvt_pk_bf16 + ds_write_b16 / ds_write_b16_d16_hi per step instead of two conversions (instruction selection)
# baseline (speedup 1.0000x reference)
.LBB0_208:
	s_add_i32 s12, s10, s11
	v_mov_b32_e32 v17, s12
	ds_read_b128 v[26:29], v17
	ds_read_b128 v[30:33], v17 offset:16
	ds_read_b128 v[38:41], v17 offset:32
	ds_read_b128 v[92:95], v17 offset:48
	s_addk_i32 s11, 0x200
	s_waitcnt lgkmcnt(0)
	v_pk_fma_f32 v[18:19], v[26:27], v[82:83], 0 op_sel_hi:[0,1,0]
	s_waitcnt lgkmcnt(2)
	v_pk_fma_f32 v[22:23], v[30:31], v[64:65], 0 op_sel_hi:[0,1,0]
	s_waitcnt lgkmcnt(1)
	v_pk_fma_f32 v[18:19], v[38:39], v[56:57], v[18:19] op_sel_hi:[0,1,1]
	s_waitcnt lgkmcnt(0)
	v_pk_fma_f32 v[22:23], v[92:93], v[48:49], v[22:23] op_sel_hi:[0,1,1]
	v_pk_fma_f32 v[18:19], v[26:27], v[62:63], v[18:19] op_sel:[1,0,0]
	v_pk_fma_f32 v[22:23], v[30:31], v[50:51], v[22:23] op_sel:[1,0,0]
	v_pk_fma_f32 v[18:19], v[38:39], v[42:43], v[18:19] op_sel:[1,0,0]
	v_pk_fma_f32 v[22:23], v[92:93], v[34:35], v[22:23] op_sel:[1,0,0]
	v_pk_fma_f32 v[18:19], v[28:29], v[58:59], v[18:19] op_sel_hi:[0,1,1]
	v_pk_fma_f32 v[22:23], v[32:33], v[54:55], v[22:23] op_sel_hi:[0,1,1]
	v_pk_fma_f32 v[18:19], v[40:41], v[46:47], v[18:19] op_sel_hi:[0,1,1]
	v_pk_fma_f32 v[22:23], v[94:95], v[84:85], v[22:23] op_sel_hi:[0,1,1]
	v_pk_fma_f32 v[18:19], v[28:29], v[60:61], v[18:19] op_sel:[1,0,0]
	v_pk_fma_f32 v[22:23], v[32:33], v[52:53], v[22:23] op_sel:[1,0,0]
	v_pk_fma_f32 v[18:19], v[40:41], v[44:45], v[18:19] op_sel:[1,0,0]
	v_pk_fma_f32 v[22:23], v[94:95], v[36:37], v[22:23] op_sel:[1,0,0]
	v_pk_mul_f32 v[26:27], v[80:81], v[76:77] op_sel:[0,1] op_sel_hi:[1,0]
	v_pk_add_f32 v[18:19], v[18:19], v[22:23]
	v_pk_fma_f32 v[22:23], v[78:79], v[76:77], v[26:27] neg_lo:[0,0,1] neg_hi:[0,0,1]
	v_pk_fma_f32 v[26:27], v[78:79], v[76:77], v[26:27]
	s_cmpk_eq_i32 s11, 0x400
	v_mov_b32_e32 v23, v27
	v_pk_add_f32 v[18:19], v[22:23], v[18:19]
	s_nop 0
	v_cvt_pk_bf16_f32 v22, v18, v19
	ds_write_b16 v16, v22
	ds_write_b16_d16_hi v16, v22 offset:128
	ds_read_b128 v[26:29], v17 offset:64
	ds_read_b128 v[30:33], v17 offset:80
	ds_read_b128 v[38:41], v17 offset:96
	ds_read_b128 v[92:95], v17 offset:112
	s_waitcnt lgkmcnt(0)
	v_pk_fma_f32 v[22:23], v[26:27], v[82:83], 0 op_sel_hi:[0,1,0]
	s_waitcnt lgkmcnt(2)
	v_pk_fma_f32 v[76:77], v[30:31], v[64:65], 0 op_sel_hi:[0,1,0]
	s_waitcnt lgkmcnt(1)
	v_pk_fma_f32 v[22:23], v[38:39], v[56:57], v[22:23] op_sel_hi:[0,1,1]
	s_waitcnt lgkmcnt(0)
	v_pk_fma_f32 v[76:77], v[92:93], v[48:49], v[76:77] op_sel_hi:[0,1,1]
	v_pk_fma_f32 v[22:23], v[26:27], v[62:63], v[22:23] op_sel:[1,0,0]
	v_pk_fma_f32 v[26:27], v[30:31], v[50:51], v[76:77] op_sel:[1,0,0]
	v_pk_fma_f32 v[22:23], v[38:39], v[42:43], v[22:23] op_sel:[1,0,0]
	v_pk_fma_f32 v[26:27], v[92:93], v[34:35], v[26:27] op_sel:[1,0,0]
	v_pk_fma_f32 v[22:23], v[28:29], v[58:59], v[22:23] op_sel_hi:[0,1,1]
	v_pk_fma_f32 v[26:27], v[32:33], v[54:55], v[26:27] op_sel_hi:[0,1,1]
	v_pk_fma_f32 v[22:23], v[40:41], v[46:47], v[22:23] op_sel_hi:[0,1,1]
	v_pk_fma_f32 v[26:27], v[94:95], v[84:85], v[26:27] op_sel_hi:[0,1,1]
	v_pk_fma_f32 v[22:23], v[28:29], v[60:61], v[22:23] op_sel:[1,0,0]
	v_pk_fma_f32 v[26:27], v[32:33], v[52:53], v[26:27] op_sel:[1,0,0]
	v_pk_fma_f32 v[22:23], v[40:41], v[44:45], v[22:23] op_sel:[1,0,0]
	v_pk_fma_f32 v[26:27], v[94:95], v[36:37], v[26:27] op_sel:[1,0,0]
	v_pk_mul_f32 v[28:29], v[80:81], v[18:19] op_sel:[0,1] op_sel_hi:[1,0]
	v_pk_add_f32 v[22:23], v[22:23], v[26:27]
	v_pk_fma_f32 v[26:27], v[78:79], v[18:19], v[28:29] neg_lo:[0,0,1] neg_hi:[0,0,1]
	v_pk_fma_f32 v[18:19], v[78:79], v[18:19], v[28:29]
	s_nop 0
	v_mov_b32_e32 v27, v19
	v_pk_add_f32 v[18:19], v[26:27], v[22:23]
	s_nop 0
	v_cvt_pk_bf16_f32 v22, v18, v19
	ds_write_b16 v16, v22 offset:272
	ds_write_b16_d16_hi v16, v22 offset:400
	ds_read_b128 v[26:29], v17 offset:128
	ds_read_b128 v[30:33], v17 offset:144
	ds_read_b128 v[38:41], v17 offset:160
	ds_read_b128 v[92:95], v17 offset:176
	s_waitcnt lgkmcnt(0)
	v_pk_fma_f32 v[22:23], v[26:27], v[82:83], 0 op_sel_hi:[0,1,0]
	s_waitcnt lgkmcnt(2)
	v_pk_fma_f32 v[76:77], v[30:31], v[64:65], 0 op_sel_hi:[0,1,0]
	s_waitcnt lgkmcnt(1)
	v_pk_fma_f32 v[22:23], v[38:39], v[56:57], v[22:23] op_sel_hi:[0,1,1]
	s_waitcnt lgkmcnt(0)
	v_pk_fma_f32 v[76:77], v[92:93], v[48:49], v[76:77] op_sel_hi:[0,1,1]
	v_pk_fma_f32 v[22:23], v[26:27], v[62:63], v[22:23] op_sel:[1,0,0]
	v_pk_fma_f32 v[26:27], v[30:31], v[50:51], v[76:77] op_sel:[1,0,0]
	v_pk_fma_f32 v[22:23], v[38:39], v[42:43], v[22:23] op_sel:[1,0,0]
	v_pk_fma_f32 v[26:27], v[92:93], v[34:35], v[26:27] op_sel:[1,0,0]
	v_pk_fma_f32 v[22:23], v[28:29], v[58:59], v[22:23] op_sel_hi:[0,1,1]
	v_pk_fma_f32 v[26:27], v[32:33], v[54:55], v[26:27] op_sel_hi:[0,1,1]
	v_pk_fma_f32 v[22:23], v[40:41], v[46:47], v[22:23] op_sel_hi:[0,1,1]
	v_pk_fma_f32 v[26:27], v[94:95], v[84:85], v[26:27] op_sel_hi:[0,1,1]
	v_pk_fma_f32 v[22:23], v[28:29], v[60:61], v[22:23] op_sel:[1,0,0]
	v_pk_fma_f32 v[26:27], v[32:33], v[52:53], v[26:27] op_sel:[1,0,0]
	v_pk_fma_f32 v[22:23], v[40:41], v[44:45], v[22:23] op_sel:[1,0,0]
	v_pk_fma_f32 v[26:27], v[94:95], v[36:37], v[26:27] op_sel:[1,0,0]
	v_pk_mul_f32 v[28:29], v[80:81], v[18:19] op_sel:[0,1] op_sel_hi:[1,0]
	v_pk_add_f32 v[22:23], v[22:23], v[26:27]
	v_pk_fma_f32 v[26:27], v[78:79], v[18:19], v[28:29] neg_lo:[0,0,1] neg_hi:[0,0,1]
	v_pk_fma_f32 v[18:19], v[78:79], v[18:19], v[28:29]
	s_nop 0
	v_mov_b32_e32 v27, v19
	v_pk_add_f32 v[18:19], v[26:27], v[22:23]
	s_nop 0
	v_cvt_pk_bf16_f32 v22, v18, v19
	ds_write_b16 v16, v22 offset:544
	ds_write_b16_d16_hi v16, v22 offset:672
	ds_read_b128 v[26:29], v17 offset:192
	ds_read_b128 v[30:33], v17 offset:208
	ds_read_b128 v[38:41], v17 offset:224
	ds_read_b128 v[92:95], v17 offset:240
	s_waitcnt lgkmcnt(0)
	v_pk_fma_f32 v[22:23], v[26:27], v[82:83], 0 op_sel_hi:[0,1,0]
	s_waitcnt lgkmcnt(2)
	v_pk_fma_f32 v[76:77], v[30:31], v[64:65], 0 op_sel_hi:[0,1,0]
	s_waitcnt lgkmcnt(1)
	v_pk_fma_f32 v[22:23], v[38:39], v[56:57], v[22:23] op_sel_hi:[0,1,1]
	s_waitcnt lgkmcnt(0)
	v_pk_fma_f32 v[76:77], v[92:93], v[48:49], v[76:77] op_sel_hi:[0,1,1]
	v_pk_fma_f32 v[22:23], v[26:27], v[62:63], v[22:23] op_sel:[1,0,0]
	v_pk_fma_f32 v[26:27], v[30:31], v[50:51], v[76:77] op_sel:[1,0,0]
	v_pk_fma_f32 v[22:23], v[38:39], v[42:43], v[22:23] op_sel:[1,0,0]
	v_pk_fma_f32 v[26:27], v[92:93], v[34:35], v[26:27] op_sel:[1,0,0]
	v_pk_fma_f32 v[22:23], v[28:29], v[58:59], v[22:23] op_sel_hi:[0,1,1]
	v_pk_fma_f32 v[26:27], v[32:33], v[54:55], v[26:27] op_sel_hi:[0,1,1]
	v_pk_fma_f32 v[22:23], v[40:41], v[46:47], v[22:23] op_sel_hi:[0,1,1]
	v_pk_fma_f32 v[26:27], v[94:95], v[84:85], v[26:27] op_sel_hi:[0,1,1]
	v_pk_fma_f32 v[22:23], v[28:29], v[60:61], v[22:23] op_sel:[1,0,0]
	v_pk_fma_f32 v[26:27], v[32:33], v[52:53], v[26:27] op_sel:[1,0,0]
	v_pk_fma_f32 v[22:23], v[40:41], v[44:45], v[22:23] op_sel:[1,0,0]
	v_pk_fma_f32 v[26:27], v[94:95], v[36:37], v[26:27] op_sel:[1,0,0]
	v_pk_mul_f32 v[28:29], v[80:81], v[18:19] op_sel:[0,1] op_sel_hi:[1,0]
	v_pk_add_f32 v[22:23], v[22:23], v[26:27]
	v_pk_fma_f32 v[26:27], v[78:79], v[18:19], v[28:29] neg_lo:[0,0,1] neg_hi:[0,0,1]
	v_pk_fma_f32 v[18:19], v[78:79], v[18:19], v[28:29]
	s_nop 0
	v_mov_b32_e32 v27, v19
	v_pk_add_f32 v[18:19], v[26:27], v[22:23]
	s_nop 0
	v_cvt_pk_bf16_f32 v22, v18, v19
	ds_write_b16 v16, v22 offset:816
	ds_write_b16_d16_hi v16, v22 offset:944
	ds_read_b128 v[26:29], v17 offset:256
	ds_read_b128 v[30:33], v17 offset:272
	ds_read_b128 v[38:41], v17 offset:288
	ds_read_b128 v[92:95], v17 offset:304
	s_waitcnt lgkmcnt(0)
	v_pk_fma_f32 v[22:23], v[26:27], v[82:83], 0 op_sel_hi:[0,1,0]
	s_waitcnt lgkmcnt(2)
	v_pk_fma_f32 v[76:77], v[30:31], v[64:65], 0 op_sel_hi:[0,1,0]
	s_waitcnt lgkmcnt(1)
	v_pk_fma_f32 v[22:23], v[38:39], v[56:57], v[22:23] op_sel_hi:[0,1,1]
	s_waitcnt lgkmcnt(0)
	v_pk_fma_f32 v[76:77], v[92:93], v[48:49], v[76:77] op_sel_hi:[0,1,1]
	v_pk_fma_f32 v[22:23], v[26:27], v[62:63], v[22:23] op_sel:[1,0,0]
	v_pk_fma_f32 v[26:27], v[30:31], v[50:51], v[76:77] op_sel:[1,0,0]
	v_pk_fma_f32 v[22:23], v[38:39], v[42:43], v[22:23] op_sel:[1,0,0]
	v_pk_fma_f32 v[26:27], v[92:93], v[34:35], v[26:27] op_sel:[1,0,0]
	v_pk_fma_f32 v[22:23], v[28:29], v[58:59], v[22:23] op_sel_hi:[0,1,1]
	v_pk_fma_f32 v[26:27], v[32:33], v[54:55], v[26:27] op_sel_hi:[0,1,1]
	v_pk_fma_f32 v[22:23], v[40:41], v[46:47], v[22:23] op_sel_hi:[0,1,1]
	v_pk_fma_f32 v[26:27], v[94:95], v[84:85], v[26:27] op_sel_hi:[0,1,1]
	v_pk_fma_f32 v[22:23], v[28:29], v[60:61], v[22:23] op_sel:[1,0,0]
	v_pk_fma_f32 v[26:27], v[32:33], v[52:53], v[26:27] op_sel:[1,0,0]
	v_pk_fma_f32 v[22:23], v[40:41], v[44:45], v[22:23] op_sel:[1,0,0]
	v_pk_fma_f32 v[26:27], v[94:95], v[36:37], v[26:27] op_sel:[1,0,0]
	v_pk_mul_f32 v[28:29], v[80:81], v[18:19] op_sel:[0,1] op_sel_hi:[1,0]
	v_pk_add_f32 v[22:23], v[22:23], v[26:27]
	v_pk_fma_f32 v[26:27], v[78:79], v[18:19], v[28:29] neg_lo:[0,0,1] neg_hi:[0,0,1]
	v_pk_fma_f32 v[18:19], v[78:79], v[18:19], v[28:29]
	s_nop 0
	v_mov_b32_e32 v27, v19
	v_pk_add_f32 v[18:19], v[26:27], v[22:23]
	s_nop 0
	v_cvt_pk_bf16_f32 v22, v18, v19
	ds_write_b16 v16, v22 offset:1088
	ds_write_b16_d16_hi v16, v22 offset:1216
	ds_read_b128 v[26:29], v17 offset:320
	ds_read_b128 v[30:33], v17 offset:336
	ds_read_b128 v[38:41], v17 offset:352
	ds_read_b128 v[92:95], v17 offset:368
	s_waitcnt lgkmcnt(0)
	v_pk_fma_f32 v[22:23], v[26:27], v[82:83], 0 op_sel_hi:[0,1,0]
	s_waitcnt lgkmcnt(2)
	v_pk_fma_f32 v[76:77], v[30:31], v[64:65], 0 op_sel_hi:[0,1,0]
	s_waitcnt lgkmcnt(1)
	v_pk_fma_f32 v[22:23], v[38:39], v[56:57], v[22:23] op_sel_hi:[0,1,1]
	s_waitcnt lgkmcnt(0)
	v_pk_fma_f32 v[76:77], v[92:93], v[48:49], v[76:77] op_sel_hi:[0,1,1]
	v_pk_fma_f32 v[22:23], v[26:27], v[62:63], v[22:23] op_sel:[1,0,0]
	v_pk_fma_f32 v[26:27], v[30:31], v[50:51], v[76:77] op_sel:[1,0,0]
	v_pk_fma_f32 v[22:23], v[38:39], v[42:43], v[22:23] op_sel:[1,0,0]
	v_pk_fma_f32 v[26:27], v[92:93], v[34:35], v[26:27] op_sel:[1,0,0]
	v_pk_fma_f32 v[22:23], v[28:29], v[58:59], v[22:23] op_sel_hi:[0,1,1]
	v_pk_fma_f32 v[26:27], v[32:33], v[54:55], v[26:27] op_sel_hi:[0,1,1]
	v_pk_fma_f32 v[22:23], v[40:41], v[46:47], v[22:23] op_sel_hi:[0,1,1]
	v_pk_fma_f32 v[26:27], v[94:95], v[84:85], v[26:27] op_sel_hi:[0,1,1]
	v_pk_fma_f32 v[22:23], v[28:29], v[60:61], v[22:23] op_sel:[1,0,0]
	v_pk_fma_f32 v[26:27], v[32:33], v[52:53], v[26:27] op_sel:[1,0,0]
	v_pk_fma_f32 v[22:23], v[40:41], v[44:45], v[22:23] op_sel:[1,0,0]
	v_pk_fma_f32 v[26:27], v[94:95], v[36:37], v[26:27] op_sel:[1,0,0]
	v_pk_mul_f32 v[28:29], v[80:81], v[18:19] op_sel:[0,1] op_sel_hi:[1,0]
	v_pk_add_f32 v[22:23], v[22:23], v[26:27]
	v_pk_fma_f32 v[26:27], v[78:79], v[18:19], v[28:29] neg_lo:[0,0,1] neg_hi:[0,0,1]
	v_pk_fma_f32 v[18:19], v[78:79], v[18:19], v[28:29]
	s_nop 0
	v_mov_b32_e32 v27, v19
	v_pk_add_f32 v[18:19], v[26:27], v[22:23]
	s_nop 0
	v_cvt_pk_bf16_f32 v22, v18, v19
	ds_write_b16 v16, v22 offset:1360
	ds_write_b16_d16_hi v16, v22 offset:1488
	ds_read_b128 v[26:29], v17 offset:384
	ds_read_b128 v[30:33], v17 offset:400
	ds_read_b128 v[38:41], v17 offset:416
	ds_read_b128 v[92:95], v17 offset:432
	s_waitcnt lgkmcnt(0)
	v_pk_fma_f32 v[22:23], v[26:27], v[82:83], 0 op_sel_hi:[0,1,0]
	s_waitcnt lgkmcnt(2)
	v_pk_fma_f32 v[76:77], v[30:31], v[64:65], 0 op_sel_hi:[0,1,0]
	s_waitcnt lgkmcnt(1)
	v_pk_fma_f32 v[22:23], v[38:39], v[56:57], v[22:23] op_sel_hi:[0,1,1]
	s_waitcnt lgkmcnt(0)
	v_pk_fma_f32 v[76:77], v[92:93], v[48:49], v[76:77] op_sel_hi:[0,1,1]
	v_pk_fma_f32 v[22:23], v[26:27], v[62:63], v[22:23] op_sel:[1,0,0]
	v_pk_fma_f32 v[26:27], v[30:31], v[50:51], v[76:77] op_sel:[1,0,0]
	v_pk_fma_f32 v[22:23], v[38:39], v[42:43], v[22:23] op_sel:[1,0,0]
	v_pk_fma_f32 v[26:27], v[92:93], v[34:35], v[26:27] op_sel:[1,0,0]
	v_pk_fma_f32 v[22:23], v[28:29], v[58:59], v[22:23] op_sel_hi:[0,1,1]
	v_pk_fma_f32 v[26:27], v[32:33], v[54:55], v[26:27] op_sel_hi:[0,1,1]
	v_pk_fma_f32 v[22:23], v[40:41], v[46:47], v[22:23] op_sel_hi:[0,1,1]
	v_pk_fma_f32 v[26:27], v[94:95], v[84:85], v[26:27] op_sel_hi:[0,1,1]
	v_pk_fma_f32 v[22:23], v[28:29], v[60:61], v[22:23] op_sel:[1,0,0]
	v_pk_fma_f32 v[26:27], v[32:33], v[52:53], v[26:27] op_sel:[1,0,0]
	v_pk_fma_f32 v[22:23], v[40:41], v[44:45], v[22:23] op_sel:[1,0,0]
	v_pk_fma_f32 v[26:27], v[94:95], v[36:37], v[26:27] op_sel:[1,0,0]
	v_pk_mul_f32 v[28:29], v[80:81], v[18:19] op_sel:[0,1] op_sel_hi:[1,0]
	v_pk_add_f32 v[22:23], v[22:23], v[26:27]
	v_pk_fma_f32 v[26:27], v[78:79], v[18:19], v[28:29] neg_lo:[0,0,1] neg_hi:[0,0,1]
	v_pk_fma_f32 v[18:19], v[78:79], v[18:19], v[28:29]
	s_nop 0
	v_mov_b32_e32 v27, v19
	v_pk_add_f32 v[18:19], v[26:27], v[22:23]
	s_nop 0
	v_cvt_pk_bf16_f32 v22, v18, v19
	ds_write_b16 v16, v22 offset:1632
	ds_write_b16_d16_hi v16, v22 offset:1760
	ds_read_b128 v[26:29], v17 offset:448
	ds_read_b128 v[30:33], v17 offset:464
	ds_read_b128 v[38:41], v17 offset:480
	ds_read_b128 v[92:95], v17 offset:496
	s_waitcnt lgkmcnt(0)
	v_pk_fma_f32 v[22:23], v[26:27], v[82:83], 0 op_sel_hi:[0,1,0]
	s_waitcnt lgkmcnt(2)
	v_pk_fma_f32 v[76:77], v[30:31], v[64:65], 0 op_sel_hi:[0,1,0]
	s_waitcnt lgkmcnt(1)
	v_pk_fma_f32 v[22:23], v[38:39], v[56:57], v[22:23] op_sel_hi:[0,1,1]
	s_waitcnt lgkmcnt(0)
	v_pk_fma_f32 v[76:77], v[92:93], v[48:49], v[76:77] op_sel_hi:[0,1,1]
	v_pk_fma_f32 v[22:23], v[26:27], v[62:63], v[22:23] op_sel:[1,0,0]
	v_pk_fma_f32 v[26:27], v[30:31], v[50:51], v[76:77] op_sel:[1,0,0]
	v_pk_fma_f32 v[22:23], v[38:39], v[42:43], v[22:23] op_sel:[1,0,0]
	v_pk_fma_f32 v[26:27], v[92:93], v[34:35], v[26:27] op_sel:[1,0,0]
	v_pk_fma_f32 v[22:23], v[28:29], v[58:59], v[22:23] op_sel_hi:[0,1,1]
	v_pk_fma_f32 v[26:27], v[32:33], v[54:55], v[26:27] op_sel_hi:[0,1,1]
	v_pk_fma_f32 v[22:23], v[40:41], v[46:47], v[22:23] op_sel_hi:[0,1,1]
	v_pk_fma_f32 v[26:27], v[94:95], v[84:85], v[26:27] op_sel_hi:[0,1,1]
	v_pk_fma_f32 v[22:23], v[28:29], v[60:61], v[22:23] op_sel:[1,0,0]
	v_pk_fma_f32 v[26:27], v[32:33], v[52:53], v[26:27] op_sel:[1,0,0]
	v_pk_fma_f32 v[22:23], v[40:41], v[44:45], v[22:23] op_sel:[1,0,0]
	v_pk_fma_f32 v[26:27], v[94:95], v[36:37], v[26:27] op_sel:[1,0,0]
	v_pk_mul_f32 v[28:29], v[80:81], v[18:19] op_sel:[0,1] op_sel_hi:[1,0]
	v_pk_add_f32 v[22:23], v[22:23], v[26:27]
	v_pk_fma_f32 v[26:27], v[78:79], v[18:19], v[28:29] neg_lo:[0,0,1] neg_hi:[0,0,1]
	v_pk_fma_f32 v[18:19], v[78:79], v[18:19], v[28:29]
	s_nop 0
	v_mov_b32_e32 v27, v19
	v_pk_add_f32 v[76:77], v[26:27], v[22:23]
	s_nop 0
	v_cvt_pk_bf16_f32 v17, v76, v77
	ds_write_b16 v16, v17 offset:1904
	ds_write_b16_d16_hi v16, v17 offset:2032
	v_add_u32_e32 v16, 0x880, v16
	s_cbranch_scc0 .LBB0_208
	ds_read_b128 v[16:19], v90
	ds_read_b128 v[26:29], v90 offset:64
	v_lshl_or_b32 v25, s6, 4, v87
	v_or_b32_e32 v22, s8, v25
	v_mov_b32_e32 v23, s9
	s_add_i32 s6, s6, 1
	s_addk_i32 s10, 0x400
	s_cmp_eq_u32 s6, 4
	s_waitcnt lgkmcnt(0)
	v_mfma_f32_16x16x32_bf16 v[16:19], v[16:19], v[0:3], 0
	s_waitcnt lgkmcnt(0)
	v_mfma_f32_16x16x32_bf16 v[16:19], v[26:29], v[4:7], v[16:19]
	ds_read_b128 v[26:29], v90 offset:128
	s_waitcnt lgkmcnt(0)
	v_mfma_f32_16x16x32_bf16 v[16:19], v[26:29], v[8:11], v[16:19]
	ds_read_b128 v[26:29], v90 offset:192
	s_waitcnt lgkmcnt(0)
	v_mfma_f32_16x16x32_bf16 v[16:19], v[26:29], v[12:15], v[16:19]
	v_lshl_add_u32 v26, v25, 6, v88
	ds_read_b32 v26, v26 offset:34816
	s_waitcnt lgkmcnt(0)
	s_nop 4
	v_fma_f32 v16, v24, v26, v16
	v_mul_f32_e32 v26, 0x3d372713, v16
	v_mul_f32_e32 v26, v16, v26
	v_fma_f32 v26, v16, v26, v16
	v_mul_f32_e32 v26, 0x3f4c422a, v26
	v_mul_f32_e32 v26, -2.0, v26
	v_mul_f32_e32 v26, 0x3fb8aa3b, v26
	v_exp_f32_e32 v26, v26
	s_nop 0
	v_add_f32_e32 v26, 1.0, v26
	v_rcp_f32_e32 v26, v26
	s_nop 0
	v_mul_f32_e32 v16, v16, v26
	v_lshlrev_b64 v[26:27], 10, v[22:23]
	v_cvt_pk_bf16_f32 v16, v16, s0
	v_lshl_add_u64 v[26:27], v[20:21], 0, v[26:27]
	flat_store_short v[26:27], v16
	v_or_b32_e32 v16, 1, v25
	v_or_b32_e32 v22, s8, v16
	v_lshl_add_u32 v16, v16, 6, v88
	ds_read_b32 v16, v16 offset:34816
	s_waitcnt lgkmcnt(0)
	v_fma_f32 v16, v24, v16, v17
	v_mul_f32_e32 v17, 0x3d372713, v16
	v_mul_f32_e32 v17, v16, v17
	v_fma_f32 v17, v16, v17, v16
	v_mul_f32_e32 v17, 0x3f4c422a, v17
	v_mul_f32_e32 v17, -2.0, v17
	v_mul_f32_e32 v17, 0x3fb8aa3b, v17
	v_exp_f32_e32 v17, v17
	s_nop 0
	v_add_f32_e32 v17, 1.0, v17
	v_rcp_f32_e32 v17, v17
	s_nop 0
	v_mul_f32_e32 v16, v16, v17
	v_cvt_pk_bf16_f32 v26, v16, s0
	v_lshlrev_b64 v[16:17], 10, v[22:23]
	v_lshl_add_u64 v[16:17], v[20:21], 0, v[16:17]
	flat_store_short v[16:17], v26
	v_or_b32_e32 v16, 2, v25
	v_or_b32_e32 v22, s8, v16
	v_lshl_add_u32 v16, v16, 6, v88
	ds_read_b32 v16, v16 offset:34816
	s_waitcnt lgkmcnt(0)
	v_fma_f32 v16, v24, v16, v18
	v_mul_f32_e32 v17, 0x3d372713, v16
	v_mul_f32_e32 v17, v16, v17
	v_fma_f32 v17, v16, v17, v16
	v_mul_f32_e32 v17, 0x3f4c422a, v17
	v_mul_f32_e32 v17, -2.0, v17
	v_mul_f32_e32 v17, 0x3fb8aa3b, v17
	v_exp_f32_e32 v17, v17
	s_nop 0
	v_add_f32_e32 v17, 1.0, v17
	v_rcp_f32_e32 v17, v17
	s_nop 0
	v_mul_f32_e32 v16, v16, v17
	v_cvt_pk_bf16_f32 v18, v16, s0
	v_lshlrev_b64 v[16:17], 10, v[22:23]
	v_lshl_add_u64 v[16:17], v[20:21], 0, v[16:17]
	flat_store_short v[16:17], v18
	v_or_b32_e32 v16, 3, v25
	v_or_b32_e32 v22, s8, v16
	v_lshl_add_u32 v16, v16, 6, v88
	ds_read_b32 v16, v16 offset:34816
	s_waitcnt lgkmcnt(0)
	v_fmac_f32_e32 v19, v24, v16
	v_mul_f32_e32 v16, 0x3d372713, v19
	v_mul_f32_e32 v16, v19, v16
	v_fma_f32 v16, v19, v16, v19
	v_mul_f32_e32 v16, 0x3f4c422a, v16
	v_mul_f32_e32 v16, -2.0, v16
	v_mul_f32_e32 v16, 0x3fb8aa3b, v16
	v_exp_f32_e32 v16, v16
	s_nop 0
	v_add_f32_e32 v16, 1.0, v16
	v_rcp_f32_e32 v16, v16
	s_nop 0
	v_mul_f32_e32 v16, v19, v16
	v_cvt_pk_bf16_f32 v18, v16, s0
	v_lshlrev_b64 v[16:17], 10, v[22:23]
	v_lshl_add_u64 v[16:17], v[20:21], 0, v[16:17]
	flat_store_short v[16:17], v18
	s_cbranch_scc0 .LBB0_207
	s_mov_b32 s12, 0
	s_mov_b32 s6, s23
	s_branch .LBB0_162
